# attention PV: split packed v_pk_mul accumulator rescale into scalar v_mul pairs between MFMAs (asm guide 7.5), on top of v30
# speedup vs baseline: 1.0069x; 1.0069x over previous
; #define LAS __attribute__((address_space(3)))
; __device__ __forceinline__ unsigned pk2(float lo, float hi) { unsigned r; asm("v_cvt_pk_bf16_f32 %0, %1, %2" : "=v"(r) : "v"(lo), "v"(hi)); return r; }
; __device__ __forceinline__ void phase_attn(const DArgs& a, LAS unsigned char* lds) {
;     ...
;                 tmax = fmaxf(tmax, __shfl_xor(tmax, 16)); tmax = fmaxf(tmax, __shfl_xor(tmax, 32));
;                 const float mnew = fmaxf(mrun, tmax), alpha = __expf(mrun - mnew); mrun = mnew;
;                 float psum = 0.f;
; #pragma unroll
;                 for (int kt = 0; kt < 4; ++kt)
; #pragma unroll
;                     for (int r = 0; r < 4; ++r) { const float p_ = __expf(sacc[kt][r] - mnew); sacc[kt][r] = p_; psum += p_; }
;                 lrun = lrun * alpha + psum;
; #pragma unroll
;                 for (int n = 0; n < 8; ++n) oacc[n] = oacc[n] * alpha;
; #pragma unroll
;                 for (int j = 0; j < 2; ++j) {
;                     u32x4 pw; pw.x = pk2(sacc[2 * j][0], sacc[2 * j][1]); pw.y = pk2(sacc[2 * j][2], sacc[2 * j][3]); pw.z = pk2(sacc[2 * j + 1][0], sacc[2 * j + 1][1]); pw.w = pk2(sacc[2 * j + 1][2], sacc[2 * j + 1][3]);
;                     const bf16x8 pf = __builtin_bit_cast(bf16x8, pw);
; #pragma unroll
;                     for (int n = 0; n < 8; ++n) {
;                         const u32x2 v0 = *(const LAS u32x2*)(lds + A_V + (16 * n + fr) * VT_LD + (32 * j + 4 * g) * 2);
;                         const u32x2 v1 = *(const LAS u32x2*)(lds + A_V + (16 * n + fr) * VT_LD + (32 * j + 16 + 4 * g) * 2);
;                         const bf16x8 vf = __builtin_bit_cast(bf16x8, (u32x4){v0.x, v0.y, v1.x, v1.y});
;                         oacc[n] = __builtin_amdgcn_mfma_f32_16x16x32_bf16(vf, pf, oacc[n], 0, 0, 0);
;                     }
.Lattn_join:
	v_and_b32_e32 v150, 64, v142
	v_xor_b32_e32 v147, 16, v142
	v_add_u32_e32 v150, 64, v150
	v_cmp_lt_i32_e32 vcc, v147, v150
	v_add_u32_e32 v171, 0x5800, v137
	v_add_u32_e32 v172, 0x6800, v137
	v_cndmask_b32_e32 v147, v142, v147, vcc
	v_lshlrev_b32_e32 v147, 2, v147
	ds_bpermute_b32 v147, v147, v80
	v_add_u32_e32 v170, 0x5000, v137
	v_add_u32_e32 v174, 0x7800, v137
	v_add_u32_e32 v175, 0x8000, v137
	v_add_u32_e32 v173, 0x7000, v137
	s_waitcnt lgkmcnt(0)
	v_max_f32_e32 v147, v147, v147
	v_max_f32_e32 v80, v80, v147
	v_xor_b32_e32 v147, 32, v142
	v_cmp_lt_i32_e32 vcc, v147, v150
	s_nop 1
	v_cndmask_b32_e32 v147, v142, v147, vcc
	v_lshlrev_b32_e32 v147, 2, v147
	ds_bpermute_b32 v147, v147, v80
	s_waitcnt lgkmcnt(0)
	ds_read2_b64 v[182:185], v165 offset0:128 offset1:132
	ds_read2_b64 v[186:189], v169 offset0:160 offset1:164
	ds_read2_b64 v[190:193], v171 offset0:224 offset1:228
	ds_read2_b64 v[194:197], v170 offset0:192 offset1:196
	ds_read2_b64 v[198:201], v172 offset1:4
	ds_read2_b64 v[202:205], v174 offset0:64 offset1:68
	ds_read2_b64 v[206:209], v175 offset0:96 offset1:100
	ds_read2_b64 v[210:213], v173 offset0:32 offset1:36
	ds_read2_b64 v[214:217], v165 offset0:136 offset1:140
	ds_read2_b64 v[218:221], v169 offset0:168 offset1:172
	ds_read2_b64 v[222:225], v170 offset0:200 offset1:204
	ds_read2_b64 v[226:229], v171 offset0:232 offset1:236
	ds_read2_b64 v[230:233], v172 offset0:8 offset1:12
	ds_read2_b64 v[234:237], v173 offset0:40 offset1:44
	ds_read2_b64 v[238:241], v174 offset0:72 offset1:76
	ds_read2_b64 v[242:245], v175 offset0:104 offset1:108
	v_max3_f32 v147, v148, v80, v147
	v_sub_f32_e32 v82, v82, v147
	v_mul_f32_e32 v82, 0x3fb8aa3b, v82
	v_exp_f32_e32 v153, v82
	v_sub_f32_e32 v82, v83, v147
	v_mul_f32_e32 v82, 0x3fb8aa3b, v82
	v_exp_f32_e32 v154, v82
	v_sub_f32_e32 v82, v84, v147
	v_mul_f32_e32 v82, 0x3fb8aa3b, v82
	v_exp_f32_e32 v155, v82
	v_sub_f32_e32 v82, v85, v147
	v_mul_f32_e32 v82, 0x3fb8aa3b, v82
	v_exp_f32_e32 v156, v82
	v_sub_f32_e32 v82, v86, v147
	v_mul_f32_e32 v82, 0x3fb8aa3b, v82
	v_exp_f32_e32 v157, v82
	v_sub_f32_e32 v82, v87, v147
	v_mul_f32_e32 v82, 0x3fb8aa3b, v82
	v_exp_f32_e32 v158, v82
	v_sub_f32_e32 v82, v92, v147
	v_mul_f32_e32 v82, 0x3fb8aa3b, v82
	v_exp_f32_e32 v159, v82
	v_sub_f32_e32 v82, v93, v147
	v_mul_f32_e32 v82, 0x3fb8aa3b, v82
	v_exp_f32_e32 v160, v82
	v_sub_f32_e32 v82, v94, v147
	v_mul_f32_e32 v82, 0x3fb8aa3b, v82
	v_exp_f32_e32 v94, v82
	v_sub_f32_e32 v82, v95, v147
	v_mul_f32_e32 v82, 0x3fb8aa3b, v82
	v_exp_f32_e32 v95, v82
	v_sub_f32_e32 v82, v88, v147
	v_mul_f32_e32 v82, 0x3fb8aa3b, v82
	v_exp_f32_e32 v161, v82
	v_sub_f32_e32 v82, v89, v147
	v_mul_f32_e32 v82, 0x3fb8aa3b, v82
	v_exp_f32_e32 v162, v82
	v_sub_f32_e32 v82, v90, v147
	v_mul_f32_e32 v82, 0x3fb8aa3b, v82
	v_exp_f32_e32 v163, v82
	v_sub_f32_e32 v82, v91, v147
	v_mul_f32_e32 v164, 0x3fb8aa3b, v82
	s_nop 0
	s_nop 0
	v_sub_f32_e32 v80, v148, v147
	v_sub_f32_e32 v81, v81, v147
	v_mul_f32_e32 v80, 0x3fb8aa3b, v80
	v_mul_f32_e32 v81, 0x3fb8aa3b, v81
	v_exp_f32_e32 v81, v81
	v_exp_f32_e32 v80, v80
	v_sub_f32_e32 v148, v149, v147
	v_mul_f32_e32 v148, 0x3fb8aa3b, v148
	v_exp_f32_e32 v152, v148
	v_mul_f32_e32 v62, v80, v62
	v_mul_f32_e32 v63, v80, v63
	v_mul_f32_e32 v60, v80, v60
	v_mul_f32_e32 v61, v80, v61
	v_mul_f32_e32 v58, v80, v58
	v_mul_f32_e32 v59, v80, v59
	v_mul_f32_e32 v56, v80, v56
	v_mul_f32_e32 v57, v80, v57
	v_cvt_pk_bf16_f32 v86, v152, v81
	v_cvt_pk_bf16_f32 v87, v153, v154
	v_cvt_pk_bf16_f32 v88, v155, v156
	v_cvt_pk_bf16_f32 v89, v157, v158
	v_mul_f32_e32 v50, v80, v50
	v_mul_f32_e32 v51, v80, v51
	s_waitcnt lgkmcnt(15)
	v_mfma_f32_16x16x32_bf16 v[60:63], v[182:185], v[86:89], v[60:63]
	s_nop 0
	v_mul_f32_e32 v48, v80, v48
	v_mul_f32_e32 v49, v80, v49
	s_nop 0
	s_waitcnt lgkmcnt(14)
	v_mfma_f32_16x16x32_bf16 v[56:59], v[186:189], v[86:89], v[56:59]
	s_nop 0
	v_mul_f32_e32 v46, v80, v46
	v_mul_f32_e32 v47, v80, v47
	v_mul_f32_e32 v44, v80, v44
	v_mul_f32_e32 v45, v80, v45
	s_waitcnt lgkmcnt(13)
	v_mfma_f32_16x16x32_bf16 v[48:51], v[190:193], v[86:89], v[48:51]
	s_nop 0
	v_mul_f32_e32 v54, v80, v54
	v_mul_f32_e32 v55, v80, v55
	v_mul_f32_e32 v52, v80, v52
	v_mul_f32_e32 v53, v80, v53
	s_waitcnt lgkmcnt(11)
	v_mfma_f32_16x16x32_bf16 v[44:47], v[198:201], v[86:89], v[44:47]
	s_nop 0
	v_mul_f32_e32 v38, v80, v38
	v_mul_f32_e32 v39, v80, v39
	v_mul_f32_e32 v36, v80, v36
	v_mul_f32_e32 v37, v80, v37
	v_mfma_f32_16x16x32_bf16 v[52:55], v[194:197], v[86:89], v[52:55]
	s_nop 0
	v_mul_f32_e32 v34, v80, v34
	v_mul_f32_e32 v35, v80, v35
	v_mul_f32_e32 v32, v80, v32
	v_mul_f32_e32 v33, v80, v33
	s_waitcnt lgkmcnt(10)
	v_mfma_f32_16x16x32_bf16 v[36:39], v[202:205], v[86:89], v[36:39]
	s_nop 0
	v_mul_f32_e32 v42, v80, v42
	v_mul_f32_e32 v43, v80, v43
	v_mul_f32_e32 v40, v80, v40
	v_mul_f32_e32 v41, v80, v41
	s_waitcnt lgkmcnt(9)
	v_mfma_f32_16x16x32_bf16 v[32:35], v[206:209], v[86:89], v[32:35]
	s_nop 0
	v_exp_f32_e32 v164, v164
	s_waitcnt lgkmcnt(8)
	v_mfma_f32_16x16x32_bf16 v[40:43], v[210:213], v[86:89], v[40:43]
	v_cvt_pk_bf16_f32 v86, v159, v160
	v_cvt_pk_bf16_f32 v87, v94, v95
	v_cvt_pk_bf16_f32 v88, v161, v162
	v_cvt_pk_bf16_f32 v89, v163, v164
	s_nop 0
	s_waitcnt lgkmcnt(7)
	v_mfma_f32_16x16x32_bf16 v[60:63], v[214:217], v[86:89], v[60:63]
	v_add_f32_e32 v82, 0, v152
	v_add_f32_e32 v81, v81, v82
	s_nop 0
	s_waitcnt lgkmcnt(6)
	v_mfma_f32_16x16x32_bf16 v[56:59], v[218:221], v[86:89], v[56:59]
	s_nop 0
	v_add_f32_e32 v81, v153, v81
	v_add_f32_e32 v81, v154, v81
	v_add_f32_e32 v81, v155, v81
	s_waitcnt lgkmcnt(5)
	v_mfma_f32_16x16x32_bf16 v[52:55], v[222:225], v[86:89], v[52:55]
	v_add_f32_e32 v81, v156, v81
	s_nop 0
	v_add_f32_e32 v81, v157, v81
	s_waitcnt lgkmcnt(4)
	v_mfma_f32_16x16x32_bf16 v[48:51], v[226:229], v[86:89], v[48:51]
	s_nop 0
	v_add_f32_e32 v81, v158, v81
	v_add_f32_e32 v81, v159, v81
	s_waitcnt lgkmcnt(3)
	v_mfma_f32_16x16x32_bf16 v[44:47], v[230:233], v[86:89], v[44:47]
	s_nop 0
	v_add_f32_e32 v81, v160, v81
	v_add_f32_e32 v81, v94, v81
	v_add_f32_e32 v81, v95, v81
	v_add_f32_e32 v81, v161, v81
	v_add_f32_e32 v81, v162, v81
	s_waitcnt lgkmcnt(2)
	v_mfma_f32_16x16x32_bf16 v[40:43], v[234:237], v[86:89], v[40:43]
	v_add_f32_e32 v81, v163, v81
	v_add_f32_e32 v81, v164, v81
	v_fmac_f32_e32 v81, v99, v80
	s_waitcnt lgkmcnt(1)
	v_mfma_f32_16x16x32_bf16 v[36:39], v[238:241], v[86:89], v[36:39]
	v_mov_b32_e32 v99, v81
	v_mov_b32_e32 v148, v147
	s_waitcnt lgkmcnt(0)
	v_mfma_f32_16x16x32_bf16 v[32:35], v[242:245], v[86:89], v[32:35]
